# speedup vs baseline: 1.0169x; 1.0088x over previous
.LBB0_818:
	s_waitcnt lgkmcnt(9)
	v_pk_mul_f32 v[196:197], v[16:17], v[130:131]
	v_pk_mul_f32 v[198:199], v[18:19], v[132:133]
	v_pk_fma_f32 v[196:197], v[20:21], v[126:127], v[196:197]
	v_pk_fma_f32 v[198:199], v[22:23], v[128:129], v[198:199]
	v_pk_mul_f32 v[130:131], v[24:25], v[130:131]
	v_pk_add_f32 v[196:197], v[196:197], v[198:199]
	v_pk_fma_f32 v[126:127], v[28:29], v[126:127], v[130:131]
	v_add_f32_e32 v196, v196, v197
	v_pk_mul_f32 v[130:131], v[26:27], v[132:133]
	ds_read_b128 v[166:169], v97 offset:24576
	ds_read_b128 v[170:173], v97 offset:24592
	ds_read_b128 v[150:153], v97 offset:32768
	ds_read_b128 v[134:137], v97 offset:32784
	ds_read_b128 v[158:161], v97 offset:40960
	ds_read_b128 v[146:149], v97 offset:40976
	ds_read_b128 v[162:165], v97 offset:8192
	ds_read_b128 v[154:157], v97 offset:8208
	ds_read_b128 v[138:141], v97
	ds_read_b128 v[142:145], v97 offset:16
	ds_read_b64 v[194:195], v244
	v_add_f32_dpp v196, v196, v196 quad_perm:[1,0,3,2] row_mask:0xf bank_mask:0xf bound_ctrl:1
	v_pk_fma_f32 v[128:129], v[30:31], v[128:129], v[130:131]
	s_nop 0
	v_add_f32_dpp v196, v196, v196 quad_perm:[2,3,0,1] row_mask:0xf bank_mask:0xf bound_ctrl:1
	v_pk_add_f32 v[126:127], v[126:127], v[128:129]
	s_nop 0
	v_add_f32_dpp v196, v196, v196 row_half_mirror row_mask:0xf bank_mask:0xf bound_ctrl:1
	s_waitcnt lgkmcnt(14)
	v_pk_mul_f32 v[128:129], v[118:119], v[196:197] op_sel_hi:[1,0] neg_lo:[0,1] neg_hi:[0,1]
	v_add_f32_e32 v126, v126, v127
	s_waitcnt lgkmcnt(11)
	v_pk_fma_f32 v[128:129], v[122:123], v[192:193], v[128:129] op_sel_hi:[1,0,1]
	s_nop 0
	v_pk_fma_f32 v[128:129], v[20:21], v[98:99], v[128:129]
	v_pk_mul_f32 v[20:21], v[120:121], v[196:197] op_sel_hi:[1,0] neg_lo:[0,1] neg_hi:[0,1]
	v_add_f32_dpp v126, v126, v126 quad_perm:[1,0,3,2] row_mask:0xf bank_mask:0xf bound_ctrl:1
	v_pk_fma_f32 v[20:21], v[124:125], v[192:193], v[20:21] op_sel_hi:[1,0,1]
	s_nop 0
	v_pk_fma_f32 v[130:131], v[22:23], v[100:101], v[20:21]
	v_pk_mul_f32 v[20:21], v[102:103], v[196:197] op_sel_hi:[1,0] neg_lo:[0,1] neg_hi:[0,1]
	v_add_f32_dpp v126, v126, v126 quad_perm:[2,3,0,1] row_mask:0xf bank_mask:0xf bound_ctrl:1
	v_pk_fma_f32 v[20:21], v[110:111], v[192:193], v[20:21] op_sel_hi:[1,0,1]
	s_nop 0
	v_pk_fma_f32 v[132:133], v[16:17], v[92:93], v[20:21]
	v_pk_mul_f32 v[16:17], v[104:105], v[196:197] op_sel_hi:[1,0] neg_lo:[0,1] neg_hi:[0,1]
	v_add_f32_dpp v126, v126, v126 row_half_mirror row_mask:0xf bank_mask:0xf bound_ctrl:1
	v_pk_fma_f32 v[16:17], v[112:113], v[192:193], v[16:17] op_sel_hi:[1,0,1]
	s_nop 0
	v_pk_fma_f32 v[196:197], v[18:19], v[94:95], v[16:17]
	v_pk_mul_f32 v[16:17], v[114:115], v[132:133]
	v_pk_mul_f32 v[18:19], v[116:117], v[196:197]
	v_pk_fma_f32 v[16:17], v[106:107], v[128:129], v[16:17]
	v_pk_fma_f32 v[18:19], v[108:109], v[130:131], v[18:19]
	s_nop 0
	v_pk_add_f32 v[16:17], v[16:17], v[18:19]
	v_pk_mul_f32 v[18:19], v[118:119], v[126:127] op_sel_hi:[1,0] neg_lo:[0,1] neg_hi:[0,1]
	s_nop 0
	v_pk_fma_f32 v[18:19], v[122:123], v[192:193], v[18:19] op_sel:[0,1,0]
	s_nop 0
	v_pk_fma_f32 v[28:29], v[28:29], v[98:99], v[18:19]
	v_pk_mul_f32 v[18:19], v[120:121], v[126:127] op_sel_hi:[1,0] neg_lo:[0,1] neg_hi:[0,1]
	s_nop 0
	v_pk_fma_f32 v[18:19], v[124:125], v[192:193], v[18:19] op_sel:[0,1,0]
	s_nop 0
	v_pk_fma_f32 v[30:31], v[30:31], v[100:101], v[18:19]
	v_pk_mul_f32 v[18:19], v[102:103], v[126:127] op_sel_hi:[1,0] neg_lo:[0,1] neg_hi:[0,1]
	s_nop 0
	v_pk_fma_f32 v[18:19], v[110:111], v[192:193], v[18:19] op_sel:[0,1,0]
	s_nop 0
	v_pk_fma_f32 v[24:25], v[24:25], v[92:93], v[18:19]
	v_pk_mul_f32 v[18:19], v[104:105], v[126:127] op_sel_hi:[1,0] neg_lo:[0,1] neg_hi:[0,1]
	s_nop 0
	v_pk_fma_f32 v[18:19], v[112:113], v[192:193], v[18:19] op_sel:[0,1,0]
	s_nop 0
	v_pk_fma_f32 v[26:27], v[26:27], v[94:95], v[18:19]
	v_pk_mul_f32 v[18:19], v[114:115], v[24:25]
	v_pk_mul_f32 v[20:21], v[116:117], v[26:27]
	v_pk_fma_f32 v[18:19], v[106:107], v[28:29], v[18:19]
	v_pk_fma_f32 v[20:21], v[108:109], v[30:31], v[20:21]
	s_nop 0
	v_pk_add_f32 v[18:19], v[18:19], v[20:21]
	s_nop 0
	v_add_f32_e32 v16, v16, v17
	v_add_f32_e32 v17, v18, v19
	s_nop 0
	v_add_f32_dpp v16, v16, v16 quad_perm:[1,0,3,2] row_mask:0xf bank_mask:0xf bound_ctrl:1
	v_add_f32_dpp v17, v17, v17 quad_perm:[1,0,3,2] row_mask:0xf bank_mask:0xf bound_ctrl:1
	s_nop 0
	v_add_f32_dpp v16, v16, v16 quad_perm:[2,3,0,1] row_mask:0xf bank_mask:0xf bound_ctrl:1
	v_add_f32_dpp v17, v17, v17 quad_perm:[2,3,0,1] row_mask:0xf bank_mask:0xf bound_ctrl:1
	s_nop 0
	v_add_f32_dpp v16, v16, v16 row_half_mirror row_mask:0xf bank_mask:0xf bound_ctrl:1
	v_add_f32_dpp v17, v17, v17 row_half_mirror row_mask:0xf bank_mask:0xf bound_ctrl:1
	s_and_saveexec_b64 s[0:1], s[4:5]
	ds_write_b64 v244, v[16:17] offset:42240
	s_or_b64 exec, exec, s[0:1]
	s_waitcnt lgkmcnt(9)
	v_pk_mul_f32 v[192:193], v[132:133], v[170:171]
	v_pk_mul_f32 v[198:199], v[196:197], v[172:173]
	v_pk_fma_f32 v[192:193], v[128:129], v[166:167], v[192:193]
	v_pk_fma_f32 v[198:199], v[130:131], v[168:169], v[198:199]
	v_pk_mul_f32 v[170:171], v[24:25], v[170:171]
	v_pk_add_f32 v[192:193], v[192:193], v[198:199]
	v_pk_fma_f32 v[166:167], v[28:29], v[166:167], v[170:171]
	v_add_f32_e32 v192, v192, v193
	v_pk_mul_f32 v[170:171], v[26:27], v[172:173]
	ds_read_b128 v[118:121], v97 offset:24832
	ds_read_b128 v[122:125], v97 offset:24848
	ds_read_b128 v[102:105], v97 offset:33024
	ds_read_b128 v[16:19], v97 offset:33040
	ds_read_b128 v[110:113], v97 offset:41216
	ds_read_b128 v[98:101], v97 offset:41232
	ds_read_b128 v[114:117], v97 offset:8448
	ds_read_b128 v[106:109], v97 offset:8464
	ds_read_b128 v[20:23], v97 offset:256
	ds_read_b128 v[92:95], v97 offset:272
	ds_read_b64 v[126:127], v244 offset:256
	v_add_f32_dpp v192, v192, v192 quad_perm:[1,0,3,2] row_mask:0xf bank_mask:0xf bound_ctrl:1
	v_pk_fma_f32 v[168:169], v[30:31], v[168:169], v[170:171]
	s_nop 0
	v_add_f32_dpp v192, v192, v192 quad_perm:[2,3,0,1] row_mask:0xf bank_mask:0xf bound_ctrl:1
	v_pk_add_f32 v[166:167], v[166:167], v[168:169]
	s_nop 0
	v_add_f32_dpp v192, v192, v192 row_half_mirror row_mask:0xf bank_mask:0xf bound_ctrl:1
	s_waitcnt lgkmcnt(14)
	v_pk_mul_f32 v[168:169], v[158:159], v[192:193] op_sel_hi:[1,0] neg_lo:[0,1] neg_hi:[0,1]
	v_add_f32_e32 v166, v166, v167
	s_waitcnt lgkmcnt(11)
	v_pk_fma_f32 v[168:169], v[162:163], v[194:195], v[168:169] op_sel_hi:[1,0,1]
	s_nop 0
	v_pk_fma_f32 v[128:129], v[128:129], v[150:151], v[168:169]
	v_pk_mul_f32 v[168:169], v[160:161], v[192:193] op_sel_hi:[1,0] neg_lo:[0,1] neg_hi:[0,1]
	v_add_f32_dpp v166, v166, v166 quad_perm:[1,0,3,2] row_mask:0xf bank_mask:0xf bound_ctrl:1
	v_pk_fma_f32 v[168:169], v[164:165], v[194:195], v[168:169] op_sel_hi:[1,0,1]
	s_nop 0
	v_add_f32_dpp v166, v166, v166 quad_perm:[2,3,0,1] row_mask:0xf bank_mask:0xf bound_ctrl:1
	v_pk_fma_f32 v[130:131], v[130:131], v[152:153], v[168:169]
	v_pk_mul_f32 v[168:169], v[146:147], v[192:193] op_sel_hi:[1,0] neg_lo:[0,1] neg_hi:[0,1]
	v_add_f32_dpp v166, v166, v166 row_half_mirror row_mask:0xf bank_mask:0xf bound_ctrl:1
	v_pk_fma_f32 v[168:169], v[154:155], v[194:195], v[168:169] op_sel_hi:[1,0,1]
	v_pk_mul_f32 v[158:159], v[158:159], v[166:167] op_sel_hi:[1,0] neg_lo:[0,1] neg_hi:[0,1]
	v_pk_fma_f32 v[132:133], v[132:133], v[134:135], v[168:169]
	v_pk_mul_f32 v[168:169], v[148:149], v[192:193] op_sel_hi:[1,0] neg_lo:[0,1] neg_hi:[0,1]
	v_pk_fma_f32 v[158:159], v[162:163], v[194:195], v[158:159] op_sel:[0,1,0]
	v_pk_fma_f32 v[168:169], v[156:157], v[194:195], v[168:169] op_sel_hi:[1,0,1]
	s_nop 0
	v_pk_fma_f32 v[192:193], v[196:197], v[136:137], v[168:169]
	v_pk_fma_f32 v[196:197], v[28:29], v[150:151], v[158:159]
	v_pk_mul_f32 v[28:29], v[160:161], v[166:167] op_sel_hi:[1,0] neg_lo:[0,1] neg_hi:[0,1]
	v_pk_mul_f32 v[168:169], v[142:143], v[132:133]
	v_pk_fma_f32 v[28:29], v[164:165], v[194:195], v[28:29] op_sel:[0,1,0]
	v_pk_mul_f32 v[170:171], v[144:145], v[192:193]
	v_pk_fma_f32 v[198:199], v[30:31], v[152:153], v[28:29]
	v_pk_mul_f32 v[28:29], v[146:147], v[166:167] op_sel_hi:[1,0] neg_lo:[0,1] neg_hi:[0,1]
	v_pk_fma_f32 v[168:169], v[138:139], v[128:129], v[168:169]
	v_pk_fma_f32 v[28:29], v[154:155], v[194:195], v[28:29] op_sel:[0,1,0]
	v_pk_fma_f32 v[170:171], v[140:141], v[130:131], v[170:171]
	v_pk_fma_f32 v[200:201], v[24:25], v[134:135], v[28:29]
	v_pk_mul_f32 v[24:25], v[148:149], v[166:167] op_sel_hi:[1,0] neg_lo:[0,1] neg_hi:[0,1]
	v_pk_add_f32 v[168:169], v[168:169], v[170:171]
	v_pk_fma_f32 v[24:25], v[156:157], v[194:195], v[24:25] op_sel:[0,1,0]
	s_nop 0
	v_pk_fma_f32 v[202:203], v[26:27], v[136:137], v[24:25]
	v_pk_mul_f32 v[24:25], v[142:143], v[200:201]
	v_pk_mul_f32 v[26:27], v[144:145], v[202:203]
	v_pk_fma_f32 v[24:25], v[138:139], v[196:197], v[24:25]
	v_pk_fma_f32 v[26:27], v[140:141], v[198:199], v[26:27]
	s_nop 0
	v_pk_add_f32 v[24:25], v[24:25], v[26:27]
	s_nop 0
	v_add_f32_e32 v25, v24, v25
	v_add_f32_e32 v24, v168, v169
	s_nop 0
	v_add_f32_dpp v25, v25, v25 quad_perm:[1,0,3,2] row_mask:0xf bank_mask:0xf bound_ctrl:1
	v_add_f32_dpp v24, v24, v24 quad_perm:[1,0,3,2] row_mask:0xf bank_mask:0xf bound_ctrl:1
	s_nop 0
	v_add_f32_dpp v25, v25, v25 quad_perm:[2,3,0,1] row_mask:0xf bank_mask:0xf bound_ctrl:1
	v_add_f32_dpp v24, v24, v24 quad_perm:[2,3,0,1] row_mask:0xf bank_mask:0xf bound_ctrl:1
	s_nop 0
	v_add_f32_dpp v25, v25, v25 row_half_mirror row_mask:0xf bank_mask:0xf bound_ctrl:1
	v_add_f32_dpp v24, v24, v24 row_half_mirror row_mask:0xf bank_mask:0xf bound_ctrl:1
	s_and_saveexec_b64 s[0:1], s[4:5]
	ds_write_b64 v244, v[24:25] offset:42496
	s_or_b64 exec, exec, s[0:1]
	s_waitcnt lgkmcnt(9)
	v_pk_mul_f32 v[168:169], v[132:133], v[122:123]
	v_pk_mul_f32 v[170:171], v[192:193], v[124:125]
	v_pk_fma_f32 v[168:169], v[128:129], v[118:119], v[168:169]
	v_pk_fma_f32 v[170:171], v[130:131], v[120:121], v[170:171]
	v_pk_mul_f32 v[122:123], v[200:201], v[122:123]
	v_pk_add_f32 v[168:169], v[168:169], v[170:171]
	v_pk_fma_f32 v[118:119], v[196:197], v[118:119], v[122:123]
	v_add_f32_e32 v168, v168, v169
	v_pk_mul_f32 v[122:123], v[202:203], v[124:125]
	ds_read_b128 v[158:161], v97 offset:25088
	ds_read_b128 v[162:165], v97 offset:25104
	ds_read_b128 v[28:31], v97 offset:33280
	ds_read_b128 v[24:27], v97 offset:33296
	ds_read_b128 v[150:153], v97 offset:41472
	ds_read_b128 v[142:145], v97 offset:41488
	ds_read_b128 v[154:157], v97 offset:8704
	ds_read_b128 v[146:149], v97 offset:8720
	ds_read_b128 v[134:137], v97 offset:512
	ds_read_b128 v[138:141], v97 offset:528
	ds_read_b64 v[166:167], v244 offset:512
	v_add_f32_dpp v168, v168, v168 quad_perm:[1,0,3,2] row_mask:0xf bank_mask:0xf bound_ctrl:1
	v_pk_fma_f32 v[120:121], v[198:199], v[120:121], v[122:123]
	s_nop 0
	v_add_f32_dpp v168, v168, v168 quad_perm:[2,3,0,1] row_mask:0xf bank_mask:0xf bound_ctrl:1
	v_pk_add_f32 v[118:119], v[118:119], v[120:121]
	s_nop 0
	v_add_f32_dpp v194, v168, v168 row_half_mirror row_mask:0xf bank_mask:0xf bound_ctrl:1
	v_add_f32_e32 v118, v118, v119
	s_waitcnt lgkmcnt(14)
	v_pk_mul_f32 v[120:121], v[110:111], v[194:195] op_sel_hi:[1,0] neg_lo:[0,1] neg_hi:[0,1]
	v_add_f32_dpp v118, v118, v118 quad_perm:[1,0,3,2] row_mask:0xf bank_mask:0xf bound_ctrl:1
	s_waitcnt lgkmcnt(11)
	v_pk_fma_f32 v[120:121], v[114:115], v[126:127], v[120:121] op_sel_hi:[1,0,1]
	v_add_f32_dpp v118, v118, v118 quad_perm:[2,3,0,1] row_mask:0xf bank_mask:0xf bound_ctrl:1
	v_pk_fma_f32 v[168:169], v[128:129], v[102:103], v[120:121]
	v_pk_mul_f32 v[120:121], v[112:113], v[194:195] op_sel_hi:[1,0] neg_lo:[0,1] neg_hi:[0,1]
	v_add_f32_dpp v118, v118, v118 row_half_mirror row_mask:0xf bank_mask:0xf bound_ctrl:1
	v_pk_fma_f32 v[120:121], v[116:117], v[126:127], v[120:121] op_sel_hi:[1,0,1]
	v_pk_mul_f32 v[110:111], v[110:111], v[118:119] op_sel_hi:[1,0] neg_lo:[0,1] neg_hi:[0,1]
	v_pk_fma_f32 v[170:171], v[130:131], v[104:105], v[120:121]
	v_pk_mul_f32 v[120:121], v[98:99], v[194:195] op_sel_hi:[1,0] neg_lo:[0,1] neg_hi:[0,1]
	v_pk_mul_f32 v[98:99], v[98:99], v[118:119] op_sel_hi:[1,0] neg_lo:[0,1] neg_hi:[0,1]
	v_pk_fma_f32 v[120:121], v[106:107], v[126:127], v[120:121] op_sel_hi:[1,0,1]
	v_pk_fma_f32 v[98:99], v[106:107], v[126:127], v[98:99] op_sel:[0,1,0]
	v_pk_fma_f32 v[172:173], v[132:133], v[16:17], v[120:121]
	v_pk_mul_f32 v[120:121], v[100:101], v[194:195] op_sel_hi:[1,0] neg_lo:[0,1] neg_hi:[0,1]
	v_pk_fma_f32 v[110:111], v[114:115], v[126:127], v[110:111] op_sel:[0,1,0]
	v_pk_fma_f32 v[200:201], v[200:201], v[16:17], v[98:99]
	v_pk_mul_f32 v[16:17], v[100:101], v[118:119] op_sel_hi:[1,0] neg_lo:[0,1] neg_hi:[0,1]
	v_pk_fma_f32 v[120:121], v[108:109], v[126:127], v[120:121] op_sel_hi:[1,0,1]
	v_pk_fma_f32 v[196:197], v[196:197], v[102:103], v[110:111]
	v_pk_mul_f32 v[102:103], v[112:113], v[118:119] op_sel_hi:[1,0] neg_lo:[0,1] neg_hi:[0,1]
	v_pk_fma_f32 v[16:17], v[108:109], v[126:127], v[16:17] op_sel:[0,1,0]
	v_pk_fma_f32 v[194:195], v[192:193], v[18:19], v[120:121]
	v_pk_fma_f32 v[102:103], v[116:117], v[126:127], v[102:103] op_sel:[0,1,0]
	v_pk_fma_f32 v[202:203], v[202:203], v[18:19], v[16:17]
	v_pk_mul_f32 v[120:121], v[92:93], v[172:173]
	v_pk_mul_f32 v[122:123], v[94:95], v[194:195]
	v_pk_fma_f32 v[198:199], v[198:199], v[104:105], v[102:103]
	v_pk_mul_f32 v[16:17], v[92:93], v[200:201]
	v_pk_mul_f32 v[18:19], v[94:95], v[202:203]
	v_pk_fma_f32 v[120:121], v[20:21], v[168:169], v[120:121]
	v_pk_fma_f32 v[122:123], v[22:23], v[170:171], v[122:123]
	v_pk_fma_f32 v[16:17], v[20:21], v[196:197], v[16:17]
	v_pk_fma_f32 v[18:19], v[22:23], v[198:199], v[18:19]
	v_pk_add_f32 v[120:121], v[120:121], v[122:123]
	v_pk_add_f32 v[16:17], v[16:17], v[18:19]
	s_nop 0
	v_add_f32_e32 v17, v16, v17
	v_add_f32_e32 v16, v120, v121
	s_nop 0
	v_add_f32_dpp v17, v17, v17 quad_perm:[1,0,3,2] row_mask:0xf bank_mask:0xf bound_ctrl:1
	v_add_f32_dpp v16, v16, v16 quad_perm:[1,0,3,2] row_mask:0xf bank_mask:0xf bound_ctrl:1
	s_nop 0
	v_add_f32_dpp v17, v17, v17 quad_perm:[2,3,0,1] row_mask:0xf bank_mask:0xf bound_ctrl:1
	v_add_f32_dpp v16, v16, v16 quad_perm:[2,3,0,1] row_mask:0xf bank_mask:0xf bound_ctrl:1
	s_nop 0
	v_add_f32_dpp v17, v17, v17 row_half_mirror row_mask:0xf bank_mask:0xf bound_ctrl:1
	v_add_f32_dpp v16, v16, v16 row_half_mirror row_mask:0xf bank_mask:0xf bound_ctrl:1
	s_and_saveexec_b64 s[0:1], s[4:5]
	ds_write_b64 v244, v[16:17] offset:42752
	s_or_b64 exec, exec, s[0:1]
	s_and_b32 s0, s6, 0x700
	v_or_b32_e32 v16, s0, v174
	v_lshlrev_b32_e32 v16, 2, v16
	ds_read_b128 v[126:129], v16 offset:24576
	ds_read_b128 v[130:133], v16 offset:24592
	ds_read_b128 v[98:101], v16 offset:32768
	ds_read_b128 v[92:95], v16 offset:32784
	ds_read_b128 v[118:121], v16 offset:40960
	ds_read_b128 v[102:105], v16 offset:40976
	ds_read_b128 v[122:125], v16 offset:8192
	ds_read_b128 v[110:113], v16 offset:8208
	ds_read_b128 v[106:109], v16
	ds_read_b128 v[114:117], v16 offset:16
	v_lshl_add_u32 v16, s0, 2, v236
	ds_read_b64 v[192:193], v16 offset:16384
	s_waitcnt lgkmcnt(14)
	v_pk_mul_f32 v[16:17], v[172:173], v[162:163]
	v_pk_mul_f32 v[18:19], v[194:195], v[164:165]
	v_pk_fma_f32 v[16:17], v[168:169], v[158:159], v[16:17]
	v_pk_fma_f32 v[18:19], v[170:171], v[160:161], v[18:19]
	v_pk_mul_f32 v[20:21], v[202:203], v[164:165]
	v_pk_add_f32 v[16:17], v[16:17], v[18:19]
	v_pk_fma_f32 v[20:21], v[198:199], v[160:161], v[20:21]
	v_add_f32_e32 v16, v16, v17
	s_nop 1
	v_add_f32_dpp v16, v16, v16 quad_perm:[1,0,3,2] row_mask:0xf bank_mask:0xf bound_ctrl:1
	s_nop 1
	v_add_f32_dpp v16, v16, v16 quad_perm:[2,3,0,1] row_mask:0xf bank_mask:0xf bound_ctrl:1
	s_nop 1
	v_add_f32_dpp v18, v16, v16 row_half_mirror row_mask:0xf bank_mask:0xf bound_ctrl:1
	v_pk_mul_f32 v[16:17], v[200:201], v[162:163]
	s_nop 0
	v_pk_fma_f32 v[16:17], v[196:197], v[158:159], v[16:17]
	s_nop 0
	v_pk_add_f32 v[16:17], v[16:17], v[20:21]
	s_nop 0
	v_add_f32_e32 v16, v16, v17
	s_nop 1
	v_add_f32_dpp v16, v16, v16 quad_perm:[1,0,3,2] row_mask:0xf bank_mask:0xf bound_ctrl:1
	s_nop 1
	v_add_f32_dpp v16, v16, v16 quad_perm:[2,3,0,1] row_mask:0xf bank_mask:0xf bound_ctrl:1
	s_nop 1
	v_add_f32_dpp v158, v16, v16 row_half_mirror row_mask:0xf bank_mask:0xf bound_ctrl:1
	v_pk_mul_f32 v[16:17], v[150:151], v[18:19] op_sel_hi:[1,0] neg_lo:[0,1] neg_hi:[0,1]
	v_pk_mul_f32 v[150:151], v[150:151], v[158:159] op_sel_hi:[1,0] neg_lo:[0,1] neg_hi:[0,1]
	s_waitcnt lgkmcnt(11)
	v_pk_fma_f32 v[16:17], v[154:155], v[166:167], v[16:17] op_sel_hi:[1,0,1]
	v_pk_fma_f32 v[150:151], v[154:155], v[166:167], v[150:151] op_sel:[0,1,0]
	v_pk_fma_f32 v[20:21], v[168:169], v[28:29], v[16:17]
	v_pk_mul_f32 v[16:17], v[152:153], v[18:19] op_sel_hi:[1,0] neg_lo:[0,1] neg_hi:[0,1]
	v_pk_fma_f32 v[28:29], v[196:197], v[28:29], v[150:151]
	v_pk_fma_f32 v[16:17], v[156:157], v[166:167], v[16:17] op_sel_hi:[1,0,1]
	v_pk_mul_f32 v[150:151], v[152:153], v[158:159] op_sel_hi:[1,0] neg_lo:[0,1] neg_hi:[0,1]
	v_pk_fma_f32 v[22:23], v[170:171], v[30:31], v[16:17]
	v_pk_mul_f32 v[16:17], v[142:143], v[18:19] op_sel_hi:[1,0] neg_lo:[0,1] neg_hi:[0,1]
	v_pk_mul_f32 v[142:143], v[142:143], v[158:159] op_sel_hi:[1,0] neg_lo:[0,1] neg_hi:[0,1]
	v_pk_fma_f32 v[16:17], v[146:147], v[166:167], v[16:17] op_sel_hi:[1,0,1]
	v_pk_fma_f32 v[142:143], v[146:147], v[166:167], v[142:143] op_sel:[0,1,0]
	v_pk_fma_f32 v[16:17], v[172:173], v[24:25], v[16:17]
	v_pk_mul_f32 v[18:19], v[144:145], v[18:19] op_sel_hi:[1,0] neg_lo:[0,1] neg_hi:[0,1]
	v_pk_fma_f32 v[24:25], v[200:201], v[24:25], v[142:143]
	v_pk_mul_f32 v[142:143], v[144:145], v[158:159] op_sel_hi:[1,0] neg_lo:[0,1] neg_hi:[0,1]
	v_pk_fma_f32 v[18:19], v[148:149], v[166:167], v[18:19] op_sel_hi:[1,0,1]
	v_pk_fma_f32 v[142:143], v[148:149], v[166:167], v[142:143] op_sel:[0,1,0]
	v_pk_fma_f32 v[18:19], v[194:195], v[26:27], v[18:19]
	v_pk_mul_f32 v[160:161], v[138:139], v[16:17]
	v_pk_fma_f32 v[150:151], v[156:157], v[166:167], v[150:151] op_sel:[0,1,0]
	v_pk_fma_f32 v[26:27], v[202:203], v[26:27], v[142:143]
	v_pk_mul_f32 v[138:139], v[138:139], v[24:25]
	v_pk_fma_f32 v[160:161], v[134:135], v[20:21], v[160:161]
	v_pk_mul_f32 v[162:163], v[140:141], v[18:19]
	v_pk_fma_f32 v[30:31], v[198:199], v[30:31], v[150:151]
	v_pk_fma_f32 v[134:135], v[134:135], v[28:29], v[138:139]
	v_pk_mul_f32 v[138:139], v[140:141], v[26:27]
	v_pk_fma_f32 v[162:163], v[136:137], v[22:23], v[162:163]
	v_pk_fma_f32 v[136:137], v[136:137], v[30:31], v[138:139]
	v_pk_add_f32 v[160:161], v[160:161], v[162:163]
	v_pk_add_f32 v[134:135], v[134:135], v[136:137]
	s_nop 0
	v_add_f32_e32 v135, v134, v135
	v_add_f32_e32 v134, v160, v161
	s_nop 0
	v_add_f32_dpp v135, v135, v135 quad_perm:[1,0,3,2] row_mask:0xf bank_mask:0xf bound_ctrl:1
	v_add_f32_dpp v134, v134, v134 quad_perm:[1,0,3,2] row_mask:0xf bank_mask:0xf bound_ctrl:1
	s_nop 0
	v_add_f32_dpp v135, v135, v135 quad_perm:[2,3,0,1] row_mask:0xf bank_mask:0xf bound_ctrl:1
	v_add_f32_dpp v134, v134, v134 quad_perm:[2,3,0,1] row_mask:0xf bank_mask:0xf bound_ctrl:1
	s_nop 0
	v_add_f32_dpp v135, v135, v135 row_half_mirror row_mask:0xf bank_mask:0xf bound_ctrl:1
	v_add_f32_dpp v134, v134, v134 row_half_mirror row_mask:0xf bank_mask:0xf bound_ctrl:1
	s_and_saveexec_b64 s[0:1], s[4:5]
	s_cbranch_execz .LBB0_817
	ds_write_b64 v244, v[134:135] offset:43008
	s_branch .LBB0_817
